# plus: P1/P2 K-loop head vmcnt drains removed (no VGPR loads pending there), static prio 1 for waves 4-7 in attention
# baseline (speedup 1.0000x reference)
; #define PG8_STAGE(bufoff, gbase, voff) do { _Pragma("unroll") for (int _i = 0; _i < 2; ++_i) { \
;         const unsigned m0v_ = (unsigned)(uintptr_t)(lds + (bufoff) + ldsw + _i * 8192); \
;         asm volatile("s_mov_b32 m0, %0\n\ts_nop 0\n\tglobal_load_lds_dwordx4 %1, %2\n\ts_nop 1" :: "s"(m0v_), "v"((voff)[_i]), "s"((const char*)(gbase)) : "m0", "memory"); } } while (0)
; #define PG8_LDA(dst, b, h) do { _Pragma("unroll") for (int m = 0; m < 4; ++m) _Pragma("unroll") for (int k = 0; k < 2; ++k) dst[m][k] = *(const LAS bf16x8*)(lds + PG8_SA(b, h) + aoff + m * 2048 + k * 1024); } while (0)
; #define PG8_LDB(dst, b, h) do { _Pragma("unroll") for (int n = 0; n < 2; ++n) _Pragma("unroll") for (int k = 0; k < 2; ++k) dst[n][k] = *(const LAS bf16x8*)(lds + PG8_SB(b, h) + boff + n * 2048 + k * 1024); } while (0)
; #define PG8_MMA(ai, bj, At, Bt) do { _Pragma("unroll") for (int m = 0; m < 4; ++m) _Pragma("unroll") for (int n = 0; n < 2; ++n) _Pragma("unroll") for (int k = 0; k < 2; ++k) \
;         acc[ai][bj][m][n] = __builtin_amdgcn_mfma_f32_16x16x32_bf16(Bt[n][k], At[m][k], acc[ai][bj][m][n], 0, 0, 0); } while (0)
; template <class Prob, class Epi, class Sched>
; __device__ __forceinline__ void gemm_phase(LAS unsigned char* lds, const Prob& P, const Sched& S, const Epi& E) {
;     ...
;         for (int t = 0; t < nt; t += 2) {
;             const bool last = (t == nt - 2);
;             if (Epi::MID_T >= 0) { if (t == Epi::MID_T) E.mid(acc, cur, slot, wr, wc, fr, fq, lds); }
;             const char* a1 = cA + (size_t)(t + 1) * kstep;
;             const char* a2 = last ? nA : cA + (size_t)(t + 2) * kstep; const char* b2 = last ? nB : cB + (size_t)(t + 2) * kstep;
;             const char* a3 = a2 + kstep; const char* b3 = b2 + kstep;
;             PG8_LDB(B0, 0, 0); PG8_LDB(B1, 0, 1); PG8_SCHED; PG8_LDA(At, 0, 0); PG8_STAGE(PG8_SA(1, 1), a1 + hstepA, voffA);
;             PG8_WAIT_V(8); PG8_WAIT_L(0); PG8_BAR; __builtin_amdgcn_s_setprio(1); PG8_MMA(0, 0, At, B0); PG8_MMA(0, 1, At, B1); __builtin_amdgcn_s_setprio(0); PG8_BAR; PG8_SCHED;
;             PG8_LDA(At, 0, 1); PG8_STAGE(PG8_SB(0, 0), b2, voffB); PG8_STAGE(PG8_SB(0, 1), b2 + hstepB, voffB); PG8_STAGE(PG8_SA(0, 0), a2, voffA);
;             PG8_WAIT_V(8); PG8_WAIT_L(0); PG8_BAR; __builtin_amdgcn_s_setprio(1); PG8_MMA(1, 0, At, B0); PG8_MMA(1, 1, At, B1); __builtin_amdgcn_s_setprio(0); PG8_BAR; PG8_SCHED;
.LBB0_270:
	ds_read_b128 v[136:139], v163
	ds_read_b128 v[140:143], v163 offset:1024
	ds_read_b128 v[144:147], v163 offset:2048
	ds_read_b128 v[148:151], v163 offset:3072
	ds_read_b128 v[152:155], v164
	ds_read_b128 v[156:159], v164 offset:1024
	ds_read_b128 v[170:173], v164 offset:2048
	ds_read_b128 v[174:177], v164 offset:3072
	s_cmp_eq_u32 s71, 28
	s_cselect_b32 s68, s46, s15
	s_cselect_b32 s69, s47, s43
	s_cselect_b32 s54, s48, s45
	s_cselect_b32 s55, s49, s70
	s_add_u32 s6, s68, 0x80
	s_addc_u32 s7, s69, 0
	ds_read_b128 v[178:181], v165
	ds_read_b128 v[182:185], v165 offset:1024
	ds_read_b128 v[186:189], v165 offset:2048
	ds_read_b128 v[190:193], v165 offset:3072
	ds_read_b128 v[194:197], v165 offset:4096
	ds_read_b128 v[198:201], v165 offset:5120
	ds_read_b128 v[202:205], v165 offset:6144
	ds_read_b128 v[206:209], v165 offset:7168
	s_mov_b32 m0, s76
	s_nop 0
	global_load_lds_dwordx4 v1, s[4:5]
	s_nop 1
	s_nop 0
	s_mov_b32 m0, s77
	s_nop 0
	global_load_lds_dwordx4 v161, s[4:5]
	s_nop 1
	s_waitcnt vmcnt(8)
	s_waitcnt lgkmcnt(0)
	s_barrier
	s_setprio 1
	s_waitcnt lgkmcnt(7)
	v_mfma_f32_16x16x32_bf16 v[126:129], v[136:139], v[178:181], v[126:129]
	v_mfma_f32_16x16x32_bf16 v[122:125], v[144:147], v[178:181], v[122:125]
	s_waitcnt lgkmcnt(5)
	v_mfma_f32_16x16x32_bf16 v[110:113], v[136:139], v[186:189], v[110:113]
	v_mfma_f32_16x16x32_bf16 v[106:109], v[144:147], v[186:189], v[106:109]
	s_waitcnt lgkmcnt(3)
	v_mfma_f32_16x16x32_bf16 v[94:97], v[136:139], v[194:197], v[94:97]
	v_mfma_f32_16x16x32_bf16 v[90:93], v[144:147], v[194:197], v[90:93]
	s_waitcnt lgkmcnt(1)
	v_mfma_f32_16x16x32_bf16 v[78:81], v[136:139], v[202:205], v[78:81]
	v_mfma_f32_16x16x32_bf16 v[74:77], v[144:147], v[202:205], v[74:77]
	v_mfma_f32_16x16x32_bf16 v[118:121], v[152:155], v[178:181], v[118:121]
	v_mfma_f32_16x16x32_bf16 v[114:117], v[170:173], v[178:181], v[114:117]
	v_mfma_f32_16x16x32_bf16 v[102:105], v[152:155], v[186:189], v[102:105]
	v_mfma_f32_16x16x32_bf16 v[98:101], v[170:173], v[186:189], v[98:101]
	v_mfma_f32_16x16x32_bf16 v[86:89], v[152:155], v[194:197], v[86:89]
	v_mfma_f32_16x16x32_bf16 v[82:85], v[170:173], v[194:197], v[82:85]
	v_mfma_f32_16x16x32_bf16 v[70:73], v[152:155], v[202:205], v[70:73]
	v_mfma_f32_16x16x32_bf16 v[66:69], v[170:173], v[202:205], v[66:69]
	v_mfma_f32_16x16x32_bf16 v[126:129], v[140:143], v[182:185], v[126:129]
	v_mfma_f32_16x16x32_bf16 v[122:125], v[148:151], v[182:185], v[122:125]
	v_mfma_f32_16x16x32_bf16 v[110:113], v[140:143], v[190:193], v[110:113]
	v_mfma_f32_16x16x32_bf16 v[106:109], v[148:151], v[190:193], v[106:109]
	v_mfma_f32_16x16x32_bf16 v[94:97], v[140:143], v[198:201], v[94:97]
	v_mfma_f32_16x16x32_bf16 v[90:93], v[148:151], v[198:201], v[90:93]
	s_waitcnt lgkmcnt(0)
	v_mfma_f32_16x16x32_bf16 v[78:81], v[140:143], v[206:209], v[78:81]
	v_mfma_f32_16x16x32_bf16 v[74:77], v[148:151], v[206:209], v[74:77]
	v_mfma_f32_16x16x32_bf16 v[118:121], v[156:159], v[182:185], v[118:121]
	v_mfma_f32_16x16x32_bf16 v[114:117], v[174:177], v[182:185], v[114:117]
	v_mfma_f32_16x16x32_bf16 v[102:105], v[156:159], v[190:193], v[102:105]
	v_mfma_f32_16x16x32_bf16 v[98:101], v[174:177], v[190:193], v[98:101]
	v_mfma_f32_16x16x32_bf16 v[86:89], v[156:159], v[198:201], v[86:89]
	v_mfma_f32_16x16x32_bf16 v[82:85], v[174:177], v[198:201], v[82:85]
	v_mfma_f32_16x16x32_bf16 v[70:73], v[156:159], v[206:209], v[70:73]
	v_mfma_f32_16x16x32_bf16 v[66:69], v[174:177], v[206:209], v[66:69]
	s_setprio 0
	s_barrier
	ds_read_b128 v[178:181], v165 offset:16384
	ds_read_b128 v[182:185], v165 offset:17408
	ds_read_b128 v[186:189], v165 offset:18432
	ds_read_b128 v[190:193], v165 offset:19456
	ds_read_b128 v[194:197], v165 offset:20480
	ds_read_b128 v[198:201], v165 offset:21504
	ds_read_b128 v[202:205], v165 offset:22528
	ds_read_b128 v[206:209], v165 offset:23552
	s_mov_b32 m0, s34
	s_nop 0
	global_load_lds_dwordx4 v160, s[54:55]
	s_nop 1
	s_add_u32 s82, s54, 0x80000
	s_mov_b32 m0, s35
	s_nop 0
	global_load_lds_dwordx4 v162, s[54:55]
	s_nop 1
	s_addc_u32 s83, s55, 0
	s_mov_b32 m0, s53
	s_nop 0
	global_load_lds_dwordx4 v160, s[82:83]
	s_nop 1
	s_nop 0
	s_mov_b32 m0, s56
	s_nop 0
	global_load_lds_dwordx4 v162, s[82:83]
	s_nop 1
	s_nop 0
	s_mov_b32 m0, s3
	s_nop 0
	global_load_lds_dwordx4 v1, s[68:69]
	s_nop 1
	s_nop 0
	s_mov_b32 m0, s57
	s_nop 0
	global_load_lds_dwordx4 v161, s[68:69]
	s_nop 1
	s_waitcnt vmcnt(8)
	s_waitcnt lgkmcnt(0)
	s_barrier
	s_setprio 1
	s_waitcnt lgkmcnt(7)
	v_mfma_f32_16x16x32_bf16 v[62:65], v[136:139], v[178:181], v[62:65]
	v_mfma_f32_16x16x32_bf16 v[58:61], v[144:147], v[178:181], v[58:61]
	s_waitcnt lgkmcnt(5)
	v_mfma_f32_16x16x32_bf16 v[46:49], v[136:139], v[186:189], v[46:49]
	v_mfma_f32_16x16x32_bf16 v[42:45], v[144:147], v[186:189], v[42:45]
	s_waitcnt lgkmcnt(3)
	v_mfma_f32_16x16x32_bf16 v[30:33], v[136:139], v[194:197], v[30:33]
	v_mfma_f32_16x16x32_bf16 v[26:29], v[144:147], v[194:197], v[26:29]
	s_waitcnt lgkmcnt(1)
	v_mfma_f32_16x16x32_bf16 v[14:17], v[136:139], v[202:205], v[14:17]
	v_mfma_f32_16x16x32_bf16 v[10:13], v[144:147], v[202:205], v[10:13]
	v_mfma_f32_16x16x32_bf16 v[54:57], v[152:155], v[178:181], v[54:57]
	v_mfma_f32_16x16x32_bf16 v[50:53], v[170:173], v[178:181], v[50:53]
	v_mfma_f32_16x16x32_bf16 v[38:41], v[152:155], v[186:189], v[38:41]
	v_mfma_f32_16x16x32_bf16 v[34:37], v[170:173], v[186:189], v[34:37]
	v_mfma_f32_16x16x32_bf16 v[22:25], v[152:155], v[194:197], v[22:25]
	v_mfma_f32_16x16x32_bf16 v[18:21], v[170:173], v[194:197], v[18:21]
	v_mfma_f32_16x16x32_bf16 v[6:9], v[152:155], v[202:205], v[6:9]
	v_mfma_f32_16x16x32_bf16 v[2:5], v[170:173], v[202:205], v[2:5]
	v_mfma_f32_16x16x32_bf16 v[62:65], v[140:143], v[182:185], v[62:65]
	v_mfma_f32_16x16x32_bf16 v[58:61], v[148:151], v[182:185], v[58:61]
	v_mfma_f32_16x16x32_bf16 v[46:49], v[140:143], v[190:193], v[46:49]
	v_mfma_f32_16x16x32_bf16 v[42:45], v[148:151], v[190:193], v[42:45]
	v_mfma_f32_16x16x32_bf16 v[30:33], v[140:143], v[198:201], v[30:33]
	v_mfma_f32_16x16x32_bf16 v[26:29], v[148:151], v[198:201], v[26:29]
	s_waitcnt lgkmcnt(0)
	v_mfma_f32_16x16x32_bf16 v[14:17], v[140:143], v[206:209], v[14:17]
	v_mfma_f32_16x16x32_bf16 v[10:13], v[148:151], v[206:209], v[10:13]
	v_mfma_f32_16x16x32_bf16 v[54:57], v[156:159], v[182:185], v[54:57]
	v_mfma_f32_16x16x32_bf16 v[50:53], v[174:177], v[182:185], v[50:53]
	v_mfma_f32_16x16x32_bf16 v[38:41], v[156:159], v[190:193], v[38:41]
	v_mfma_f32_16x16x32_bf16 v[34:37], v[174:177], v[190:193], v[34:37]
	v_mfma_f32_16x16x32_bf16 v[22:25], v[156:159], v[198:201], v[22:25]
	v_mfma_f32_16x16x32_bf16 v[18:21], v[174:177], v[198:201], v[18:21]
	v_mfma_f32_16x16x32_bf16 v[6:9], v[156:159], v[206:209], v[6:9]
	v_mfma_f32_16x16x32_bf16 v[2:5], v[174:177], v[206:209], v[2:5]
	s_setprio 0
	s_barrier
; #define PG8_STAGE(bufoff, gbase, voff) do { _Pragma("unroll") for (int _i = 0; _i < 2; ++_i) { \
;         const unsigned m0v_ = (unsigned)(uintptr_t)(lds + (bufoff) + ldsw + _i * 8192); \
;         asm volatile("s_mov_b32 m0, %0\n\ts_nop 0\n\tglobal_load_lds_dwordx4 %1, %2\n\ts_nop 1" :: "s"(m0v_), "v"((voff)[_i]), "s"((const char*)(gbase)) : "m0", "memory"); } } while (0)
; #define PG8_LDA(dst, b, h) do { _Pragma("unroll") for (int m = 0; m < 4; ++m) _Pragma("unroll") for (int k = 0; k < 2; ++k) dst[m][k] = *(const LAS bf16x8*)(lds + PG8_SA(b, h) + aoff + m * 2048 + k * 1024); } while (0)
; #define PG8_LDB(dst, b, h) do { _Pragma("unroll") for (int n = 0; n < 2; ++n) _Pragma("unroll") for (int k = 0; k < 2; ++k) dst[n][k] = *(const LAS bf16x8*)(lds + PG8_SB(b, h) + boff + n * 2048 + k * 1024); } while (0)
; #define PG8_MMA(ai, bj, At, Bt) do { _Pragma("unroll") for (int m = 0; m < 4; ++m) _Pragma("unroll") for (int n = 0; n < 2; ++n) _Pragma("unroll") for (int k = 0; k < 2; ++k) \
;         acc[ai][bj][m][n] = __builtin_amdgcn_mfma_f32_16x16x32_bf16(Bt[n][k], At[m][k], acc[ai][bj][m][n], 0, 0, 0); } while (0)
; #define PG8_WAIT_V(n) asm volatile("s_waitcnt vmcnt(" #n ")" ::: "memory")
; #define PG8_WAIT_L(n) asm volatile("s_waitcnt lgkmcnt(" #n ")" ::: "memory")
; #define PG8_BAR __builtin_amdgcn_s_barrier()
; #define PG8_SCHED __builtin_amdgcn_sched_barrier(0)
; template <class Prob, class Epi, class Sched>
; __device__ __forceinline__ void gemm_phase(LAS unsigned char* lds, const Prob& P, const Sched& S, const Epi& E) {
;     ...
;             PG8_LDB(B0, 1, 0); PG8_LDB(B1, 1, 1); PG8_SCHED; PG8_LDA(At, 1, 0); PG8_STAGE(PG8_SA(0, 1), a2 + hstepA, voffA);
;             PG8_WAIT_V(8); PG8_WAIT_L(0); PG8_BAR; __builtin_amdgcn_s_setprio(1); PG8_MMA(0, 0, At, B0); PG8_MMA(0, 1, At, B1); __builtin_amdgcn_s_setprio(0); PG8_BAR; PG8_SCHED;
;             PG8_LDA(At, 1, 1); PG8_STAGE(PG8_SB(1, 0), b3, voffB); PG8_STAGE(PG8_SB(1, 1), b3 + hstepB, voffB); PG8_STAGE(PG8_SA(1, 0), a3, voffA);
;             PG8_WAIT_V(8); PG8_WAIT_L(0); PG8_BAR; __builtin_amdgcn_s_setprio(1); PG8_MMA(1, 0, At, B0); PG8_MMA(1, 1, At, B1); __builtin_amdgcn_s_setprio(0); PG8_BAR; PG8_SCHED;
;         }
	ds_read_b128 v[136:139], v166
	ds_read_b128 v[140:143], v166 offset:1024
	ds_read_b128 v[144:147], v166 offset:2048
	ds_read_b128 v[148:151], v166 offset:3072
	ds_read_b128 v[152:155], v167
	ds_read_b128 v[156:159], v167 offset:1024
	ds_read_b128 v[170:173], v167 offset:2048
	ds_read_b128 v[174:177], v167 offset:3072
	ds_read_b128 v[178:181], v165 offset:32768
	ds_read_b128 v[182:185], v165 offset:33792
	ds_read_b128 v[186:189], v165 offset:34816
	ds_read_b128 v[190:193], v165 offset:35840
	ds_read_b128 v[194:197], v165 offset:36864
	ds_read_b128 v[198:201], v165 offset:37888
	ds_read_b128 v[202:205], v165 offset:38912
	ds_read_b128 v[206:209], v165 offset:39936
	s_add_u32 s68, s68, 0x80000
	s_addc_u32 s69, s69, 0
	s_mov_b32 m0, s58
	s_nop 0
	global_load_lds_dwordx4 v1, s[68:69]
	s_nop 1
	s_nop 0
	s_mov_b32 m0, s59
	s_nop 0
	global_load_lds_dwordx4 v161, s[68:69]
	s_nop 1
	s_waitcnt vmcnt(8)
	s_waitcnt lgkmcnt(0)
	s_barrier
	s_setprio 1
	s_waitcnt lgkmcnt(7)
	v_mfma_f32_16x16x32_bf16 v[126:129], v[136:139], v[178:181], v[126:129]
	v_mfma_f32_16x16x32_bf16 v[122:125], v[144:147], v[178:181], v[122:125]
	s_waitcnt lgkmcnt(5)
	v_mfma_f32_16x16x32_bf16 v[110:113], v[136:139], v[186:189], v[110:113]
	v_mfma_f32_16x16x32_bf16 v[106:109], v[144:147], v[186:189], v[106:109]
	s_waitcnt lgkmcnt(3)
	v_mfma_f32_16x16x32_bf16 v[94:97], v[136:139], v[194:197], v[94:97]
	v_mfma_f32_16x16x32_bf16 v[90:93], v[144:147], v[194:197], v[90:93]
	s_waitcnt lgkmcnt(1)
	v_mfma_f32_16x16x32_bf16 v[78:81], v[136:139], v[202:205], v[78:81]
	v_mfma_f32_16x16x32_bf16 v[74:77], v[144:147], v[202:205], v[74:77]
	v_mfma_f32_16x16x32_bf16 v[118:121], v[152:155], v[178:181], v[118:121]
	v_mfma_f32_16x16x32_bf16 v[114:117], v[170:173], v[178:181], v[114:117]
	v_mfma_f32_16x16x32_bf16 v[102:105], v[152:155], v[186:189], v[102:105]
	v_mfma_f32_16x16x32_bf16 v[98:101], v[170:173], v[186:189], v[98:101]
	v_mfma_f32_16x16x32_bf16 v[86:89], v[152:155], v[194:197], v[86:89]
	v_mfma_f32_16x16x32_bf16 v[82:85], v[170:173], v[194:197], v[82:85]
	v_mfma_f32_16x16x32_bf16 v[70:73], v[152:155], v[202:205], v[70:73]
	v_mfma_f32_16x16x32_bf16 v[66:69], v[170:173], v[202:205], v[66:69]
	v_mfma_f32_16x16x32_bf16 v[126:129], v[140:143], v[182:185], v[126:129]
	v_mfma_f32_16x16x32_bf16 v[122:125], v[148:151], v[182:185], v[122:125]
	v_mfma_f32_16x16x32_bf16 v[110:113], v[140:143], v[190:193], v[110:113]
	v_mfma_f32_16x16x32_bf16 v[106:109], v[148:151], v[190:193], v[106:109]
	v_mfma_f32_16x16x32_bf16 v[94:97], v[140:143], v[198:201], v[94:97]
	v_mfma_f32_16x16x32_bf16 v[90:93], v[148:151], v[198:201], v[90:93]
	s_waitcnt lgkmcnt(0)
	v_mfma_f32_16x16x32_bf16 v[78:81], v[140:143], v[206:209], v[78:81]
	v_mfma_f32_16x16x32_bf16 v[74:77], v[148:151], v[206:209], v[74:77]
	v_mfma_f32_16x16x32_bf16 v[118:121], v[156:159], v[182:185], v[118:121]
	v_mfma_f32_16x16x32_bf16 v[114:117], v[174:177], v[182:185], v[114:117]
	v_mfma_f32_16x16x32_bf16 v[102:105], v[156:159], v[190:193], v[102:105]
	v_mfma_f32_16x16x32_bf16 v[98:101], v[174:177], v[190:193], v[98:101]
	v_mfma_f32_16x16x32_bf16 v[86:89], v[156:159], v[198:201], v[86:89]
	v_mfma_f32_16x16x32_bf16 v[82:85], v[174:177], v[198:201], v[82:85]
	v_mfma_f32_16x16x32_bf16 v[70:73], v[156:159], v[206:209], v[70:73]
	v_mfma_f32_16x16x32_bf16 v[66:69], v[174:177], v[206:209], v[66:69]
	s_setprio 0
	s_barrier
	ds_read_b128 v[178:181], v165 offset:49152
	ds_read_b128 v[182:185], v165 offset:50176
	ds_read_b128 v[186:189], v165 offset:51200
	ds_read_b128 v[190:193], v165 offset:52224
	ds_read_b128 v[194:197], v165 offset:53248
	ds_read_b128 v[198:201], v165 offset:54272
	ds_read_b128 v[202:205], v165 offset:55296
	ds_read_b128 v[206:209], v165 offset:56320
	s_add_u32 s68, s54, 0x80
	s_addc_u32 s69, s55, 0
	s_mov_b32 m0, s64
	s_nop 0
	global_load_lds_dwordx4 v160, s[68:69]
	s_nop 1
	s_add_u32 s54, s54, 0x80080
	s_mov_b32 m0, s65
	s_nop 0
	global_load_lds_dwordx4 v162, s[68:69]
	s_nop 1
	s_addc_u32 s55, s55, 0
	s_mov_b32 m0, s74
	s_nop 0
	global_load_lds_dwordx4 v160, s[54:55]
	s_nop 1
	s_nop 0
	s_mov_b32 m0, s75
	s_nop 0
	global_load_lds_dwordx4 v162, s[54:55]
	s_nop 1
	s_nop 0
	s_mov_b32 m0, s72
	s_nop 0
	global_load_lds_dwordx4 v1, s[6:7]
	s_nop 1
	s_nop 0
	s_mov_b32 m0, s73
	s_nop 0
	global_load_lds_dwordx4 v161, s[6:7]
	s_nop 1
	s_waitcnt vmcnt(8)
	s_waitcnt lgkmcnt(0)
	s_barrier
	s_setprio 1
	s_waitcnt lgkmcnt(7)
	v_mfma_f32_16x16x32_bf16 v[62:65], v[136:139], v[178:181], v[62:65]
	v_mfma_f32_16x16x32_bf16 v[58:61], v[144:147], v[178:181], v[58:61]
	s_waitcnt lgkmcnt(5)
	v_mfma_f32_16x16x32_bf16 v[46:49], v[136:139], v[186:189], v[46:49]
	v_mfma_f32_16x16x32_bf16 v[42:45], v[144:147], v[186:189], v[42:45]
	s_waitcnt lgkmcnt(3)
	v_mfma_f32_16x16x32_bf16 v[30:33], v[136:139], v[194:197], v[30:33]
	v_mfma_f32_16x16x32_bf16 v[26:29], v[144:147], v[194:197], v[26:29]
	s_waitcnt lgkmcnt(1)
	v_mfma_f32_16x16x32_bf16 v[14:17], v[136:139], v[202:205], v[14:17]
	v_mfma_f32_16x16x32_bf16 v[10:13], v[144:147], v[202:205], v[10:13]
	v_mfma_f32_16x16x32_bf16 v[54:57], v[152:155], v[178:181], v[54:57]
	v_mfma_f32_16x16x32_bf16 v[50:53], v[170:173], v[178:181], v[50:53]
	v_mfma_f32_16x16x32_bf16 v[38:41], v[152:155], v[186:189], v[38:41]
	v_mfma_f32_16x16x32_bf16 v[34:37], v[170:173], v[186:189], v[34:37]
	v_mfma_f32_16x16x32_bf16 v[22:25], v[152:155], v[194:197], v[22:25]
	v_mfma_f32_16x16x32_bf16 v[18:21], v[170:173], v[194:197], v[18:21]
	v_mfma_f32_16x16x32_bf16 v[6:9], v[152:155], v[202:205], v[6:9]
	v_mfma_f32_16x16x32_bf16 v[2:5], v[170:173], v[202:205], v[2:5]
	v_mfma_f32_16x16x32_bf16 v[62:65], v[140:143], v[182:185], v[62:65]
	v_mfma_f32_16x16x32_bf16 v[58:61], v[148:151], v[182:185], v[58:61]
	v_mfma_f32_16x16x32_bf16 v[46:49], v[140:143], v[190:193], v[46:49]
	v_mfma_f32_16x16x32_bf16 v[42:45], v[148:151], v[190:193], v[42:45]
	v_mfma_f32_16x16x32_bf16 v[30:33], v[140:143], v[198:201], v[30:33]
	v_mfma_f32_16x16x32_bf16 v[26:29], v[148:151], v[198:201], v[26:29]
	s_waitcnt lgkmcnt(0)
	v_mfma_f32_16x16x32_bf16 v[14:17], v[140:143], v[206:209], v[14:17]
	v_mfma_f32_16x16x32_bf16 v[10:13], v[148:151], v[206:209], v[10:13]
	v_mfma_f32_16x16x32_bf16 v[54:57], v[156:159], v[182:185], v[54:57]
	v_mfma_f32_16x16x32_bf16 v[50:53], v[174:177], v[182:185], v[50:53]
	v_mfma_f32_16x16x32_bf16 v[38:41], v[156:159], v[190:193], v[38:41]
	v_mfma_f32_16x16x32_bf16 v[34:37], v[174:177], v[190:193], v[34:37]
	v_mfma_f32_16x16x32_bf16 v[22:25], v[156:159], v[198:201], v[22:25]
	v_mfma_f32_16x16x32_bf16 v[18:21], v[174:177], v[198:201], v[18:21]
	v_mfma_f32_16x16x32_bf16 v[6:9], v[156:159], v[206:209], v[6:9]
	v_mfma_f32_16x16x32_bf16 v[2:5], v[174:177], v[206:209], v[2:5]
	s_setprio 0
	s_barrier
	s_add_i32 s71, s71, 2
	s_add_u32 s15, s15, 0x100
	s_addc_u32 s43, s43, 0
	s_add_u32 s45, s45, 0x100
	s_addc_u32 s70, s70, 0
	s_add_u32 s4, s4, 0x100
	s_addc_u32 s5, s5, 0
	s_cmp_gt_u32 s71, 29
	s_cbranch_scc0 .LBB0_270
	s_and_b64 vcc, exec, s[40:41]
	s_cbranch_vccz .LBB0_273
	s_barrier

; #define PG8_STAGE(bufoff, gbase, voff) do { _Pragma("unroll") for (int _i = 0; _i < 2; ++_i) { \
;         const unsigned m0v_ = (unsigned)(uintptr_t)(lds + (bufoff) + ldsw + _i * 8192); \
;         asm volatile("s_mov_b32 m0, %0\n\ts_nop 0\n\tglobal_load_lds_dwordx4 %1, %2\n\ts_nop 1" :: "s"(m0v_), "v"((voff)[_i]), "s"((const char*)(gbase)) : "m0", "memory"); } } while (0)
; #define PG8_LDA(dst, b, h) do { _Pragma("unroll") for (int m = 0; m < 4; ++m) _Pragma("unroll") for (int k = 0; k < 2; ++k) dst[m][k] = *(const LAS bf16x8*)(lds + PG8_SA(b, h) + aoff + m * 2048 + k * 1024); } while (0)
; #define PG8_LDB(dst, b, h) do { _Pragma("unroll") for (int n = 0; n < 2; ++n) _Pragma("unroll") for (int k = 0; k < 2; ++k) dst[n][k] = *(const LAS bf16x8*)(lds + PG8_SB(b, h) + boff + n * 2048 + k * 1024); } while (0)
; #define PG8_MMA(ai, bj, At, Bt) do { _Pragma("unroll") for (int m = 0; m < 4; ++m) _Pragma("unroll") for (int n = 0; n < 2; ++n) _Pragma("unroll") for (int k = 0; k < 2; ++k) \
;         acc[ai][bj][m][n] = __builtin_amdgcn_mfma_f32_16x16x32_bf16(Bt[n][k], At[m][k], acc[ai][bj][m][n], 0, 0, 0); } while (0)
; template <class Prob, class Epi, class Sched>
; __device__ __forceinline__ void gemm_phase(LAS unsigned char* lds, const Prob& P, const Sched& S, const Epi& E) {
;     ...
;         for (int t = 0; t < nt; t += 2) {
;             const bool last = (t == nt - 2);
;             if (Epi::MID_T >= 0) { if (t == Epi::MID_T) E.mid(acc, cur, slot, wr, wc, fr, fq, lds); }
;             const char* a1 = cA + (size_t)(t + 1) * kstep;
;             const char* a2 = last ? nA : cA + (size_t)(t + 2) * kstep; const char* b2 = last ? nB : cB + (size_t)(t + 2) * kstep;
;             const char* a3 = a2 + kstep; const char* b3 = b2 + kstep;
;             PG8_LDB(B0, 0, 0); PG8_LDB(B1, 0, 1); PG8_SCHED; PG8_LDA(At, 0, 0); PG8_STAGE(PG8_SA(1, 1), a1 + hstepA, voffA);
;             PG8_WAIT_V(8); PG8_WAIT_L(0); PG8_BAR; __builtin_amdgcn_s_setprio(1); PG8_MMA(0, 0, At, B0); PG8_MMA(0, 1, At, B1); __builtin_amdgcn_s_setprio(0); PG8_BAR; PG8_SCHED;
;             PG8_LDA(At, 0, 1); PG8_STAGE(PG8_SB(0, 0), b2, voffB); PG8_STAGE(PG8_SB(0, 1), b2 + hstepB, voffB); PG8_STAGE(PG8_SA(0, 0), a2, voffA);
;             PG8_WAIT_V(8); PG8_WAIT_L(0); PG8_BAR; __builtin_amdgcn_s_setprio(1); PG8_MMA(1, 0, At, B0); PG8_MMA(1, 1, At, B1); __builtin_amdgcn_s_setprio(0); PG8_BAR; PG8_SCHED;
.LBB0_451:
	v_add_u32_e32 v130, 0x10000, v219
	s_add_i32 s68, s6, 2
	ds_read_b128 v[132:135], v130
	ds_read_b128 v[136:139], v130 offset:1024
	ds_read_b128 v[140:143], v130 offset:2048
	ds_read_b128 v[144:147], v130 offset:3072
	v_add_u32_e32 v130, 0x14000, v219
	s_add_u32 s7, s78, s4
	ds_read_b128 v[148:151], v130
	ds_read_b128 v[152:155], v130 offset:1024
	ds_read_b128 v[156:159], v130 offset:2048
	ds_read_b128 v[160:163], v130 offset:3072
	s_addc_u32 s8, s79, s5
	s_add_u32 s9, s80, s4
	s_addc_u32 s74, s81, s5
	s_cmp_eq_u32 s55, s6
	s_cselect_b32 s10, s88, s7
	s_cselect_b32 s11, s89, s8
	s_cselect_b32 s8, s90, s9
	s_cselect_b32 s9, s91, s74
	s_add_u32 s6, s10, 0x80
	s_addc_u32 s7, s11, 0
	ds_read_b128 v[164:167], v220
	ds_read_b128 v[168:171], v220 offset:1024
	ds_read_b128 v[172:175], v220 offset:2048
	ds_read_b128 v[176:179], v220 offset:3072
	ds_read_b128 v[180:183], v220 offset:4096
	ds_read_b128 v[184:187], v220 offset:5120
	ds_read_b128 v[188:191], v220 offset:6144
	ds_read_b128 v[192:195], v220 offset:7168
	s_add_u32 s74, s49, s4
	s_addc_u32 s75, s54, s5
	s_add_u32 s74, s74, 0xffffff80
	s_addc_u32 s75, s75, -1
	s_mov_b32 m0, s46
	s_nop 0
	global_load_lds_dwordx4 v1, s[74:75]
	s_nop 1
	s_nop 0
	s_mov_b32 m0, s47
	s_nop 0
	global_load_lds_dwordx4 v217, s[74:75]
	s_nop 1
	s_waitcnt vmcnt(8)
	s_waitcnt lgkmcnt(0)
	s_barrier
	s_setprio 1
	s_waitcnt lgkmcnt(7)
	v_mfma_f32_16x16x32_bf16 v[2:5], v[132:135], v[164:167], v[2:5]
	v_mfma_f32_16x16x32_bf16 v[62:65], v[140:143], v[164:167], v[62:65]
	s_waitcnt lgkmcnt(5)
	v_mfma_f32_16x16x32_bf16 v[58:61], v[132:135], v[172:175], v[58:61]
	v_mfma_f32_16x16x32_bf16 v[54:57], v[140:143], v[172:175], v[54:57]
	s_waitcnt lgkmcnt(3)
	v_mfma_f32_16x16x32_bf16 v[50:53], v[132:135], v[180:183], v[50:53]
	v_mfma_f32_16x16x32_bf16 v[46:49], v[140:143], v[180:183], v[46:49]
	s_waitcnt lgkmcnt(1)
	v_mfma_f32_16x16x32_bf16 v[42:45], v[132:135], v[188:191], v[42:45]
	v_mfma_f32_16x16x32_bf16 v[38:41], v[140:143], v[188:191], v[38:41]
	v_mfma_f32_16x16x32_bf16 v[34:37], v[148:151], v[164:167], v[34:37]
	v_mfma_f32_16x16x32_bf16 v[30:33], v[156:159], v[164:167], v[30:33]
	v_mfma_f32_16x16x32_bf16 v[26:29], v[148:151], v[172:175], v[26:29]
	v_mfma_f32_16x16x32_bf16 v[22:25], v[156:159], v[172:175], v[22:25]
	v_mfma_f32_16x16x32_bf16 v[18:21], v[148:151], v[180:183], v[18:21]
	v_mfma_f32_16x16x32_bf16 v[14:17], v[156:159], v[180:183], v[14:17]
	v_mfma_f32_16x16x32_bf16 v[10:13], v[148:151], v[188:191], v[10:13]
	v_mfma_f32_16x16x32_bf16 v[6:9], v[156:159], v[188:191], v[6:9]
	v_mfma_f32_16x16x32_bf16 v[2:5], v[136:139], v[168:171], v[2:5]
	v_mfma_f32_16x16x32_bf16 v[62:65], v[144:147], v[168:171], v[62:65]
	v_mfma_f32_16x16x32_bf16 v[58:61], v[136:139], v[176:179], v[58:61]
	v_mfma_f32_16x16x32_bf16 v[54:57], v[144:147], v[176:179], v[54:57]
	v_mfma_f32_16x16x32_bf16 v[50:53], v[136:139], v[184:187], v[50:53]
	v_mfma_f32_16x16x32_bf16 v[46:49], v[144:147], v[184:187], v[46:49]
	s_waitcnt lgkmcnt(0)
	v_mfma_f32_16x16x32_bf16 v[42:45], v[136:139], v[192:195], v[42:45]
	v_mfma_f32_16x16x32_bf16 v[38:41], v[144:147], v[192:195], v[38:41]
	v_mfma_f32_16x16x32_bf16 v[34:37], v[152:155], v[168:171], v[34:37]
	v_mfma_f32_16x16x32_bf16 v[30:33], v[160:163], v[168:171], v[30:33]
	v_mfma_f32_16x16x32_bf16 v[26:29], v[152:155], v[176:179], v[26:29]
	v_mfma_f32_16x16x32_bf16 v[22:25], v[160:163], v[176:179], v[22:25]
	v_mfma_f32_16x16x32_bf16 v[18:21], v[152:155], v[184:187], v[18:21]
	v_mfma_f32_16x16x32_bf16 v[14:17], v[160:163], v[184:187], v[14:17]
	v_mfma_f32_16x16x32_bf16 v[10:13], v[152:155], v[192:195], v[10:13]
	v_mfma_f32_16x16x32_bf16 v[6:9], v[160:163], v[192:195], v[6:9]
	s_setprio 0
	s_barrier
	ds_read_b128 v[164:167], v220 offset:16384
	ds_read_b128 v[168:171], v220 offset:17408
	ds_read_b128 v[172:175], v220 offset:18432
	ds_read_b128 v[176:179], v220 offset:19456
	ds_read_b128 v[180:183], v220 offset:20480
	ds_read_b128 v[184:187], v220 offset:21504
	ds_read_b128 v[188:191], v220 offset:22528
	ds_read_b128 v[192:195], v220 offset:23552
	s_mov_b32 m0, s67
	s_nop 0
	global_load_lds_dwordx4 v216, s[8:9]
	s_nop 1
	s_add_u32 s74, s8, 0x80000
	s_mov_b32 m0, s0
	s_nop 0
	global_load_lds_dwordx4 v218, s[8:9]
	s_nop 1
	s_addc_u32 s75, s9, 0
	s_mov_b32 m0, s1
	s_nop 0
	global_load_lds_dwordx4 v216, s[74:75]
	s_nop 1
	s_nop 0
	s_mov_b32 m0, s35
	s_nop 0
	global_load_lds_dwordx4 v218, s[74:75]
	s_nop 1
	s_nop 0
	s_mov_b32 m0, s41
	s_nop 0
	global_load_lds_dwordx4 v1, s[10:11]
	s_nop 1
	s_nop 0
	s_mov_b32 m0, s3
	s_nop 0
	global_load_lds_dwordx4 v217, s[10:11]
	s_nop 1
	s_waitcnt vmcnt(8)
	s_waitcnt lgkmcnt(0)
	s_barrier
; #define PG8_STAGE(bufoff, gbase, voff) do { _Pragma("unroll") for (int _i = 0; _i < 2; ++_i) { \
;         const unsigned m0v_ = (unsigned)(uintptr_t)(lds + (bufoff) + ldsw + _i * 8192); \
;         asm volatile("s_mov_b32 m0, %0\n\ts_nop 0\n\tglobal_load_lds_dwordx4 %1, %2\n\ts_nop 1" :: "s"(m0v_), "v"((voff)[_i]), "s"((const char*)(gbase)) : "m0", "memory"); } } while (0)
; #define PG8_LDA(dst, b, h) do { _Pragma("unroll") for (int m = 0; m < 4; ++m) _Pragma("unroll") for (int k = 0; k < 2; ++k) dst[m][k] = *(const LAS bf16x8*)(lds + PG8_SA(b, h) + aoff + m * 2048 + k * 1024); } while (0)
; #define PG8_LDB(dst, b, h) do { _Pragma("unroll") for (int n = 0; n < 2; ++n) _Pragma("unroll") for (int k = 0; k < 2; ++k) dst[n][k] = *(const LAS bf16x8*)(lds + PG8_SB(b, h) + boff + n * 2048 + k * 1024); } while (0)
; #define PG8_MMA(ai, bj, At, Bt) do { _Pragma("unroll") for (int m = 0; m < 4; ++m) _Pragma("unroll") for (int n = 0; n < 2; ++n) _Pragma("unroll") for (int k = 0; k < 2; ++k) \
;         acc[ai][bj][m][n] = __builtin_amdgcn_mfma_f32_16x16x32_bf16(Bt[n][k], At[m][k], acc[ai][bj][m][n], 0, 0, 0); } while (0)
; #define PG8_WAIT_V(n) asm volatile("s_waitcnt vmcnt(" #n ")" ::: "memory")
; #define PG8_WAIT_L(n) asm volatile("s_waitcnt lgkmcnt(" #n ")" ::: "memory")
; #define PG8_BAR __builtin_amdgcn_s_barrier()
; #define PG8_SCHED __builtin_amdgcn_sched_barrier(0)
; template <class Prob, class Epi, class Sched>
; __device__ __forceinline__ void gemm_phase(LAS unsigned char* lds, const Prob& P, const Sched& S, const Epi& E) {
;     ...
;             PG8_WAIT_V(8); PG8_WAIT_L(0); PG8_BAR; __builtin_amdgcn_s_setprio(1); PG8_MMA(1, 0, At, B0); PG8_MMA(1, 1, At, B1); __builtin_amdgcn_s_setprio(0); PG8_BAR; PG8_SCHED;
;             PG8_LDB(B0, 1, 0); PG8_LDB(B1, 1, 1); PG8_SCHED; PG8_LDA(At, 1, 0); PG8_STAGE(PG8_SA(0, 1), a2 + hstepA, voffA);
;             PG8_WAIT_V(8); PG8_WAIT_L(0); PG8_BAR; __builtin_amdgcn_s_setprio(1); PG8_MMA(0, 0, At, B0); PG8_MMA(0, 1, At, B1); __builtin_amdgcn_s_setprio(0); PG8_BAR; PG8_SCHED;
	s_setprio 1
	s_waitcnt lgkmcnt(7)
	v_mfma_f32_16x16x32_bf16 v[126:129], v[132:135], v[164:167], v[126:129]
	v_mfma_f32_16x16x32_bf16 v[122:125], v[140:143], v[164:167], v[122:125]
	s_waitcnt lgkmcnt(5)
	v_mfma_f32_16x16x32_bf16 v[118:121], v[132:135], v[172:175], v[118:121]
	v_mfma_f32_16x16x32_bf16 v[114:117], v[140:143], v[172:175], v[114:117]
	s_waitcnt lgkmcnt(3)
	v_mfma_f32_16x16x32_bf16 v[110:113], v[132:135], v[180:183], v[110:113]
	v_mfma_f32_16x16x32_bf16 v[106:109], v[140:143], v[180:183], v[106:109]
	s_waitcnt lgkmcnt(1)
	v_mfma_f32_16x16x32_bf16 v[102:105], v[132:135], v[188:191], v[102:105]
	v_mfma_f32_16x16x32_bf16 v[98:101], v[140:143], v[188:191], v[98:101]
	v_mfma_f32_16x16x32_bf16 v[94:97], v[148:151], v[164:167], v[94:97]
	v_mfma_f32_16x16x32_bf16 v[90:93], v[156:159], v[164:167], v[90:93]
	v_mfma_f32_16x16x32_bf16 v[86:89], v[148:151], v[172:175], v[86:89]
	v_mfma_f32_16x16x32_bf16 v[82:85], v[156:159], v[172:175], v[82:85]
	v_mfma_f32_16x16x32_bf16 v[78:81], v[148:151], v[180:183], v[78:81]
	v_mfma_f32_16x16x32_bf16 v[74:77], v[156:159], v[180:183], v[74:77]
	v_mfma_f32_16x16x32_bf16 v[70:73], v[148:151], v[188:191], v[70:73]
	v_mfma_f32_16x16x32_bf16 v[66:69], v[156:159], v[188:191], v[66:69]
	v_mfma_f32_16x16x32_bf16 v[126:129], v[136:139], v[168:171], v[126:129]
	v_mfma_f32_16x16x32_bf16 v[122:125], v[144:147], v[168:171], v[122:125]
	v_mfma_f32_16x16x32_bf16 v[118:121], v[136:139], v[176:179], v[118:121]
	v_mfma_f32_16x16x32_bf16 v[114:117], v[144:147], v[176:179], v[114:117]
	v_mfma_f32_16x16x32_bf16 v[110:113], v[136:139], v[184:187], v[110:113]
	v_mfma_f32_16x16x32_bf16 v[106:109], v[144:147], v[184:187], v[106:109]
	s_waitcnt lgkmcnt(0)
	v_mfma_f32_16x16x32_bf16 v[102:105], v[136:139], v[192:195], v[102:105]
	v_mfma_f32_16x16x32_bf16 v[98:101], v[144:147], v[192:195], v[98:101]
	v_mfma_f32_16x16x32_bf16 v[94:97], v[152:155], v[168:171], v[94:97]
	v_mfma_f32_16x16x32_bf16 v[90:93], v[160:163], v[168:171], v[90:93]
	v_mfma_f32_16x16x32_bf16 v[86:89], v[152:155], v[176:179], v[86:89]
	v_mfma_f32_16x16x32_bf16 v[82:85], v[160:163], v[176:179], v[82:85]
	v_mfma_f32_16x16x32_bf16 v[78:81], v[152:155], v[184:187], v[78:81]
	v_mfma_f32_16x16x32_bf16 v[74:77], v[160:163], v[184:187], v[74:77]
	v_mfma_f32_16x16x32_bf16 v[70:73], v[152:155], v[192:195], v[70:73]
	v_mfma_f32_16x16x32_bf16 v[66:69], v[160:163], v[192:195], v[66:69]
	s_setprio 0
	s_barrier
	v_add_u32_e32 v130, 0x18000, v219
	ds_read_b128 v[132:135], v130
	ds_read_b128 v[136:139], v130 offset:1024
	ds_read_b128 v[140:143], v130 offset:2048
	ds_read_b128 v[144:147], v130 offset:3072
	v_add_u32_e32 v130, 0x1c000, v219
	ds_read_b128 v[148:151], v130
	ds_read_b128 v[152:155], v130 offset:1024
	ds_read_b128 v[156:159], v130 offset:2048
	ds_read_b128 v[160:163], v130 offset:3072
	ds_read_b128 v[164:167], v220 offset:32768
	ds_read_b128 v[168:171], v220 offset:33792
	ds_read_b128 v[172:175], v220 offset:34816
	ds_read_b128 v[176:179], v220 offset:35840
	ds_read_b128 v[180:183], v220 offset:36864
	ds_read_b128 v[184:187], v220 offset:37888
	ds_read_b128 v[188:191], v220 offset:38912
	ds_read_b128 v[192:195], v220 offset:39936
	s_add_u32 s10, s10, 0x80000
	s_addc_u32 s11, s11, 0
	s_mov_b32 m0, s64
	s_nop 0
	global_load_lds_dwordx4 v1, s[10:11]
	s_nop 1
	s_nop 0
	s_mov_b32 m0, s65
	s_nop 0
	global_load_lds_dwordx4 v217, s[10:11]
	s_nop 1
	s_waitcnt vmcnt(8)
	s_waitcnt lgkmcnt(0)
	s_barrier
	s_setprio 1
	s_waitcnt lgkmcnt(7)
	v_mfma_f32_16x16x32_bf16 v[2:5], v[132:135], v[164:167], v[2:5]
	v_mfma_f32_16x16x32_bf16 v[62:65], v[140:143], v[164:167], v[62:65]
	s_waitcnt lgkmcnt(5)
	v_mfma_f32_16x16x32_bf16 v[58:61], v[132:135], v[172:175], v[58:61]
	v_mfma_f32_16x16x32_bf16 v[54:57], v[140:143], v[172:175], v[54:57]
	s_waitcnt lgkmcnt(3)
	v_mfma_f32_16x16x32_bf16 v[50:53], v[132:135], v[180:183], v[50:53]
	v_mfma_f32_16x16x32_bf16 v[46:49], v[140:143], v[180:183], v[46:49]
	s_waitcnt lgkmcnt(1)
	v_mfma_f32_16x16x32_bf16 v[42:45], v[132:135], v[188:191], v[42:45]
	v_mfma_f32_16x16x32_bf16 v[38:41], v[140:143], v[188:191], v[38:41]
	v_mfma_f32_16x16x32_bf16 v[34:37], v[148:151], v[164:167], v[34:37]
	v_mfma_f32_16x16x32_bf16 v[30:33], v[156:159], v[164:167], v[30:33]
	v_mfma_f32_16x16x32_bf16 v[26:29], v[148:151], v[172:175], v[26:29]
	v_mfma_f32_16x16x32_bf16 v[22:25], v[156:159], v[172:175], v[22:25]
	v_mfma_f32_16x16x32_bf16 v[18:21], v[148:151], v[180:183], v[18:21]
	v_mfma_f32_16x16x32_bf16 v[14:17], v[156:159], v[180:183], v[14:17]
	v_mfma_f32_16x16x32_bf16 v[10:13], v[148:151], v[188:191], v[10:13]
	v_mfma_f32_16x16x32_bf16 v[6:9], v[156:159], v[188:191], v[6:9]
	v_mfma_f32_16x16x32_bf16 v[2:5], v[136:139], v[168:171], v[2:5]
	v_mfma_f32_16x16x32_bf16 v[62:65], v[144:147], v[168:171], v[62:65]
	v_mfma_f32_16x16x32_bf16 v[58:61], v[136:139], v[176:179], v[58:61]
	v_mfma_f32_16x16x32_bf16 v[54:57], v[144:147], v[176:179], v[54:57]
	v_mfma_f32_16x16x32_bf16 v[50:53], v[136:139], v[184:187], v[50:53]
	v_mfma_f32_16x16x32_bf16 v[46:49], v[144:147], v[184:187], v[46:49]
	s_waitcnt lgkmcnt(0)
	v_mfma_f32_16x16x32_bf16 v[42:45], v[136:139], v[192:195], v[42:45]
	v_mfma_f32_16x16x32_bf16 v[38:41], v[144:147], v[192:195], v[38:41]
	v_mfma_f32_16x16x32_bf16 v[34:37], v[152:155], v[168:171], v[34:37]
	v_mfma_f32_16x16x32_bf16 v[30:33], v[160:163], v[168:171], v[30:33]
	v_mfma_f32_16x16x32_bf16 v[26:29], v[152:155], v[176:179], v[26:29]
	v_mfma_f32_16x16x32_bf16 v[22:25], v[160:163], v[176:179], v[22:25]
	v_mfma_f32_16x16x32_bf16 v[18:21], v[152:155], v[184:187], v[18:21]
	v_mfma_f32_16x16x32_bf16 v[14:17], v[160:163], v[184:187], v[14:17]
	v_mfma_f32_16x16x32_bf16 v[10:13], v[152:155], v[192:195], v[10:13]
	v_mfma_f32_16x16x32_bf16 v[6:9], v[160:163], v[192:195], v[6:9]
	s_setprio 0
	s_barrier
; #define PG8_STAGE(bufoff, gbase, voff) do { _Pragma("unroll") for (int _i = 0; _i < 2; ++_i) { \
;         const unsigned m0v_ = (unsigned)(uintptr_t)(lds + (bufoff) + ldsw + _i * 8192); \
;         asm volatile("s_mov_b32 m0, %0\n\ts_nop 0\n\tglobal_load_lds_dwordx4 %1, %2\n\ts_nop 1" :: "s"(m0v_), "v"((voff)[_i]), "s"((const char*)(gbase)) : "m0", "memory"); } } while (0)
; #define PG8_LDA(dst, b, h) do { _Pragma("unroll") for (int m = 0; m < 4; ++m) _Pragma("unroll") for (int k = 0; k < 2; ++k) dst[m][k] = *(const LAS bf16x8*)(lds + PG8_SA(b, h) + aoff + m * 2048 + k * 1024); } while (0)
; #define PG8_MMA(ai, bj, At, Bt) do { _Pragma("unroll") for (int m = 0; m < 4; ++m) _Pragma("unroll") for (int n = 0; n < 2; ++n) _Pragma("unroll") for (int k = 0; k < 2; ++k) \
;         acc[ai][bj][m][n] = __builtin_amdgcn_mfma_f32_16x16x32_bf16(Bt[n][k], At[m][k], acc[ai][bj][m][n], 0, 0, 0); } while (0)
; #define PG8_WAIT_V(n) asm volatile("s_waitcnt vmcnt(" #n ")" ::: "memory")
; #define PG8_WAIT_L(n) asm volatile("s_waitcnt lgkmcnt(" #n ")" ::: "memory")
; #define PG8_BAR __builtin_amdgcn_s_barrier()
; #define PG8_SCHED __builtin_amdgcn_sched_barrier(0)
; template <class Prob, class Epi, class Sched>
; __device__ __forceinline__ void gemm_phase(LAS unsigned char* lds, const Prob& P, const Sched& S, const Epi& E) {
;     ...
;             PG8_LDA(At, 1, 1); PG8_STAGE(PG8_SB(1, 0), b3, voffB); PG8_STAGE(PG8_SB(1, 1), b3 + hstepB, voffB); PG8_STAGE(PG8_SA(1, 0), a3, voffA);
;             PG8_WAIT_V(8); PG8_WAIT_L(0); PG8_BAR; __builtin_amdgcn_s_setprio(1); PG8_MMA(1, 0, At, B0); PG8_MMA(1, 1, At, B1); __builtin_amdgcn_s_setprio(0); PG8_BAR; PG8_SCHED;
;         }
;         if (wr == 0) PG8_BAR;
	ds_read_b128 v[164:167], v220 offset:49152
	ds_read_b128 v[168:171], v220 offset:50176
	ds_read_b128 v[172:175], v220 offset:51200
	ds_read_b128 v[176:179], v220 offset:52224
	ds_read_b128 v[180:183], v220 offset:53248
	ds_read_b128 v[184:187], v220 offset:54272
	ds_read_b128 v[188:191], v220 offset:55296
	ds_read_b128 v[192:195], v220 offset:56320
	s_add_u32 s10, s8, 0x80
	s_addc_u32 s11, s9, 0
	s_mov_b32 m0, s62
	s_nop 0
	global_load_lds_dwordx4 v216, s[10:11]
	s_nop 1
	s_add_u32 s8, s8, 0x80080
	s_mov_b32 m0, s63
	s_nop 0
	global_load_lds_dwordx4 v218, s[10:11]
	s_nop 1
	s_addc_u32 s9, s9, 0
	s_mov_b32 m0, s44
	s_nop 0
	global_load_lds_dwordx4 v216, s[8:9]
	s_nop 1
	s_nop 0
	s_mov_b32 m0, s45
	s_nop 0
	global_load_lds_dwordx4 v218, s[8:9]
	s_nop 1
	s_nop 0
	s_mov_b32 m0, s70
	s_nop 0
	global_load_lds_dwordx4 v1, s[6:7]
	s_nop 1
	s_nop 0
	s_mov_b32 m0, s71
	s_nop 0
	global_load_lds_dwordx4 v217, s[6:7]
	s_nop 1
	s_waitcnt vmcnt(8)
	s_waitcnt lgkmcnt(0)
	s_barrier
	s_setprio 1
	s_waitcnt lgkmcnt(7)
	v_mfma_f32_16x16x32_bf16 v[126:129], v[132:135], v[164:167], v[126:129]
	v_mfma_f32_16x16x32_bf16 v[122:125], v[140:143], v[164:167], v[122:125]
	s_waitcnt lgkmcnt(5)
	v_mfma_f32_16x16x32_bf16 v[118:121], v[132:135], v[172:175], v[118:121]
	v_mfma_f32_16x16x32_bf16 v[114:117], v[140:143], v[172:175], v[114:117]
	s_waitcnt lgkmcnt(3)
	v_mfma_f32_16x16x32_bf16 v[110:113], v[132:135], v[180:183], v[110:113]
	v_mfma_f32_16x16x32_bf16 v[106:109], v[140:143], v[180:183], v[106:109]
	s_waitcnt lgkmcnt(1)
	v_mfma_f32_16x16x32_bf16 v[102:105], v[132:135], v[188:191], v[102:105]
	v_mfma_f32_16x16x32_bf16 v[98:101], v[140:143], v[188:191], v[98:101]
	v_mfma_f32_16x16x32_bf16 v[94:97], v[148:151], v[164:167], v[94:97]
	v_mfma_f32_16x16x32_bf16 v[90:93], v[156:159], v[164:167], v[90:93]
	v_mfma_f32_16x16x32_bf16 v[86:89], v[148:151], v[172:175], v[86:89]
	v_mfma_f32_16x16x32_bf16 v[82:85], v[156:159], v[172:175], v[82:85]
	v_mfma_f32_16x16x32_bf16 v[78:81], v[148:151], v[180:183], v[78:81]
	v_mfma_f32_16x16x32_bf16 v[74:77], v[156:159], v[180:183], v[74:77]
	v_mfma_f32_16x16x32_bf16 v[70:73], v[148:151], v[188:191], v[70:73]
	v_mfma_f32_16x16x32_bf16 v[66:69], v[156:159], v[188:191], v[66:69]
	v_mfma_f32_16x16x32_bf16 v[126:129], v[136:139], v[168:171], v[126:129]
	v_mfma_f32_16x16x32_bf16 v[122:125], v[144:147], v[168:171], v[122:125]
	v_mfma_f32_16x16x32_bf16 v[118:121], v[136:139], v[176:179], v[118:121]
	v_mfma_f32_16x16x32_bf16 v[114:117], v[144:147], v[176:179], v[114:117]
	v_mfma_f32_16x16x32_bf16 v[110:113], v[136:139], v[184:187], v[110:113]
	v_mfma_f32_16x16x32_bf16 v[106:109], v[144:147], v[184:187], v[106:109]
	s_waitcnt lgkmcnt(0)
	v_mfma_f32_16x16x32_bf16 v[102:105], v[136:139], v[192:195], v[102:105]
	v_mfma_f32_16x16x32_bf16 v[98:101], v[144:147], v[192:195], v[98:101]
	v_mfma_f32_16x16x32_bf16 v[94:97], v[152:155], v[168:171], v[94:97]
	v_mfma_f32_16x16x32_bf16 v[90:93], v[160:163], v[168:171], v[90:93]
	v_mfma_f32_16x16x32_bf16 v[86:89], v[152:155], v[176:179], v[86:89]
	v_mfma_f32_16x16x32_bf16 v[82:85], v[160:163], v[176:179], v[82:85]
	v_mfma_f32_16x16x32_bf16 v[78:81], v[152:155], v[184:187], v[78:81]
	v_mfma_f32_16x16x32_bf16 v[74:77], v[160:163], v[184:187], v[74:77]
	v_mfma_f32_16x16x32_bf16 v[70:73], v[152:155], v[192:195], v[70:73]
	v_mfma_f32_16x16x32_bf16 v[66:69], v[160:163], v[192:195], v[66:69]
	s_setprio 0
	s_barrier
	s_add_u32 s4, s4, 0x100
	s_addc_u32 s5, s5, 0
	s_cmp_ge_i32 s68, s53
	s_mov_b32 s6, s68
	s_cbranch_scc0 .LBB0_451
	v_readlane_b32 s4, v247, 39
	v_readlane_b32 s5, v247, 40
	s_and_b64 vcc, exec, s[4:5]
	s_cbranch_vccz .LBB0_454
	s_barrier

; #define LAS __attribute__((address_space(3)))
; __device__ __forceinline__ int fresh_lane() { int l; asm volatile("v_mbcnt_lo_u32_b32 %0, -1, 0\n\tv_mbcnt_hi_u32_b32 %0, -1, %0" : "=v"(l)); return l; }
; __device__ __forceinline__ int v_rd_base(int lane) { return ((lane & 3) << 3) | (((lane >> 2) & 3) << 6) | (((lane >> 4) & 1) << 5) | (((lane >> 5) & 1) << 8); }
; template <int ABL> __device__ __forceinline__ void attn_unit(int b, int h, int qb, const bf16_t* Q, const bf16_t* KV, const bf16_t* KPE, bf16_t* MG, float* ssqa, LAS unsigned char* L) {
;   const int tid = threadIdx.x, lane = fresh_lane(), r32 = lane & 31, hi = lane >> 5; const int wid = __builtin_amdgcn_readfirstlane(tid >> 6);
;   LAS unsigned char* Vl = L + OFF_V; LAS unsigned char* Kl = L + OFF_K;
;   LAS float* wsf = (LAS float*)(L + OFF_WS) + wid * 64; LAS float* li_l = wsf; LAS float* al_l = wsf + 32;
;   LAS unsigned char* Qr = (wid < 5) ? L + OFF_QR + wid * 8192 : L + OFF_QR_HI + (wid - 5) * 8192;
;   float m_reg = -1e30f, l_reg = 0; f32x16 o[4] = {}; bf16x8 qr[4];
;   const size_t rowbase = (size_t)b * SEQ; const int q0 = qb * 256;
;   const int kro = r32 * 128, ksw = (r32 >> 1) & 7;
;   const int krow = wid * 8 + (lane >> 3), kcl = (lane & 7) ^ ((krow >> 1) & 7);
;   const unsigned voffK = (unsigned)(krow * LDKV + kcl * 8) * 2u, voffP = (unsigned)(krow * LDKPE + kcl * 8) * 2u;
;   const int vj = (lane >> 2) & 7, vkg = wid >> 1, vk = (vkg >> 1) * 16 + (vj >> 2) * 8 + (vkg & 1) * 4 + (vj & 3), vc = 32 * (2 * (wid & 1) + (lane >> 5)) + (lane & 3) * 8;
;   const unsigned voffV = (unsigned)(vk * LDKV + vc) * 2u;
;   const char* Kt = (const char*)(KV + rowbase * LDKV + h * 256); const char* Pt = (const char*)(KPE + rowbase * LDKPE);
;   constexpr size_t KSTEP = (size_t)KVBLK * LDKV * 2, PSTEP = (size_t)KVBLK * LDKPE * 2;
;     ...
;   DMA_K(0, 0); DMA_V(0, 0); DMA_K(1, 1);
;   const bf16_t* Qw = Q + (rowbase + q0 + wid * QBLK + r32) * LDQ + h * 192 + hi * 8;
; #pragma unroll
;   for (int d0 = 0; d0 < 4; ++d0) qr[d0] = ld8(Qw + d0 * 16);
; #pragma unroll
;   for (int dd = 0; dd < 8; ++dd) *reinterpret_cast<LAS bf16x8*>(Qr + (dd >> 2) * 4096 + kro + (((2 * (dd & 3) + hi) ^ ksw) << 4)) = ld8(Qw + (4 + dd) * 16);
;   const int vb0 = (int)(unsigned)(uintptr_t)Vl + v_rd_base(lane);
.LBB0_746:
	v_readfirstlane_b32 s82, v0
	s_ashr_i32 s54, s2, 7
	s_lshr_b32 s58, s82, 4
	s_lshr_b32 s83, s82, 6
	s_cmp_lt_u32 s83, 4
	s_cbranch_scc1 .Lattn_prio_done
	s_setprio 1
.Lattn_prio_done:
	s_ashr_i32 s55, s54, 31
	s_lshl_b32 s6, s2, 8
	s_and_b32 s84, s58, 0xffff0
	s_lshr_b32 s58, s82, 5
	s_bfe_u32 s56, s2, 0x30004
	v_mbcnt_lo_u32_b32 v56, -1, 0
	v_mbcnt_hi_u32_b32 v56, -1, v56
	s_lshl_b32 s57, s83, 13
	v_ashrrev_i32_e32 v164, 5, v56
	s_lshl_b64 s[0:1], s[54:55], 12
	s_and_b32 s6, s6, 0xf00
	s_and_b32 s85, s58, 4
	s_and_b32 s58, s58, 2
	s_lshl_b64 s[72:73], s[54:55], 24
	v_ashrrev_i32_e32 v57, 3, v56
	v_add_u32_e32 v6, s58, v164
	s_add_u32 s58, s36, s72
	v_lshl_add_u32 v4, s83, 3, v57
	s_addc_u32 s59, s37, s73
	s_lshl_b32 s60, s56, 9
	v_lshrrev_b32_e32 v2, 1, v4
	s_add_u32 s70, s58, s60
	v_xor_b32_e32 v2, v2, v56
	s_addc_u32 s71, s59, 0
	s_lshl_b64 s[74:75], s[54:55], 19
	v_lshlrev_b32_e32 v2, 4, v2
	s_add_u32 s54, s22, s74
	v_and_b32_e32 v58, 0x70, v2
	s_addc_u32 s55, s23, s75
	s_lshl_b32 s86, s83, 10
	v_lshrrev_b32_e32 v1, 1, v56
	v_lshl_or_b32 v2, v4, 12, v58
	s_add_i32 s58, s86, 0
	v_and_b32_e32 v59, 8, v1
	v_bfe_u32 v60, v56, 2, 2
	v_lshlrev_b32_e32 v62, 4, v56
	s_add_i32 s59, s58, 0x8000
	v_lshl_add_u64 v[52:53], s[70:71], 0, v[2:3]
	s_mov_b64 s[60:61], 0x80
	v_or3_b32 v5, v59, v60, s84
	v_and_b32_e32 v61, 48, v62
	s_mov_b32 m0, s59
	v_lshl_add_u64 v[8:9], v[52:53], 0, s[60:61]
	s_add_i32 s60, s58, 0xa000
	v_or_b32_e32 v5, s85, v5
	v_lshl_or_b32 v6, v6, 6, v61
	global_load_lds_dwordx4 v2, s[70:71]
	s_mov_b32 m0, s60
	s_add_i32 s61, s58, 0xc000
	v_lshl_or_b32 v4, v4, 7, v58
	v_lshl_add_u32 v6, v5, 12, v6
	global_load_lds_dwordx4 v[8:9], off
	v_mov_b32_e32 v5, v3
	s_mov_b32 m0, s61
	v_mov_b32_e32 v7, v3
	v_lshl_add_u64 v[54:55], s[54:55], 0, v[4:5]
	global_load_lds_dwordx4 v4, s[54:55]
	v_lshl_add_u64 v[142:143], s[70:71], 0, v[6:7]
	s_mov_b64 s[54:55], 0x100
	v_lshl_add_u64 v[4:5], v[142:143], 0, s[54:55]
	s_mov_b32 m0, s58
	s_mov_b64 s[54:55], 0x20100
	s_add_i32 s77, s58, 0x2000
	global_load_lds_dwordx4 v[4:5], off
	v_lshl_add_u64 v[4:5], v[142:143], 0, s[54:55]
	s_mov_b32 m0, s77
	s_add_i32 s78, s58, 0xe000
	s_mov_b64 s[54:55], 0x40000
	global_load_lds_dwordx4 v[4:5], off
	v_lshl_add_u64 v[4:5], v[52:53], 0, s[54:55]
	s_mov_b32 m0, s78
	s_mov_b64 s[54:55], 0x40080
	global_load_lds_dwordx4 v[4:5], off
	v_lshl_add_u64 v[4:5], v[52:53], 0, s[54:55]
	s_add_i32 m0, s58, 0x10000
	s_or_b32 s0, s0, s6
	global_load_lds_dwordx4 v[4:5], off
	s_add_i32 m0, s58, 0x12000
	s_lshl_b32 s6, s83, 5
	v_and_b32_e32 v163, 31, v56
	s_mov_b64 s[54:55], 0x2000
	s_add_u32 s70, s0, s6
	v_lshl_add_u64 v[4:5], v[54:55], 0, s[54:55]
	v_or_b32_e32 v2, s70, v163
	s_movk_i32 s0, 0xc00
	global_load_lds_dwordx4 v[4:5], off
	s_addc_u32 s71, s1, 0
	v_mad_u64_u32 v[4:5], s[0:1], v2, s0, v[138:139]
	v_mad_i32_i24 v5, s71, v141, v5
	s_mul_i32 s6, s56, 0x180
	v_lshlrev_b32_e32 v6, 3, v164
	v_lshl_add_u64 v[4:5], v[4:5], 0, s[6:7]
	v_ashrrev_i32_e32 v7, 31, v6
	v_lshl_add_u64 v[8:9], v[6:7], 1, v[4:5]
	global_load_dwordx4 v[126:129], v[8:9], off
	global_load_dwordx4 v[122:125], v[8:9], off offset:32
	global_load_dwordx4 v[118:121], v[8:9], off offset:64
	global_load_dwordx4 v[114:117], v[8:9], off offset:96
	global_load_dwordx4 v[4:7], v[8:9], off offset:128
	s_add_i32 s6, s57, 0
	s_cmpk_lt_u32 s82, 0x140
	s_mov_b32 s0, 0x14800
	s_cselect_b32 s0, s0, 0x16400
	s_add_i32 s0, s6, s0
	v_lshlrev_b32_e32 v63, 7, v163
	v_bitop3_b32 v10, v1, v164, 7 bitop3:0x6c
	v_add_u32_e32 v2, s0, v63
	v_lshlrev_b32_e32 v172, 4, v10
	v_add_u32_e32 v171, v2, v172
	v_add_u32_e32 v10, 2, v164
	v_bitop3_b32 v10, v10, v1, 7 bitop3:0x78
	v_lshlrev_b32_e32 v173, 4, v10
	v_add_u32_e32 v170, v2, v173
	v_add_u32_e32 v10, 4, v164
	v_bitop3_b32 v10, v10, v1, 7 bitop3:0x78
	v_lshlrev_b32_e32 v174, 4, v10
	v_add_u32_e32 v169, v2, v174
	v_add_u32_e32 v10, 6, v164
	v_bitop3_b32 v1, v10, v1, 7 bitop3:0x78
	v_lshlrev_b32_e32 v175, 4, v1
	v_add_u32_e32 v168, v2, v175
	v_add_u32_e32 v1, 0, v63
	v_add_u32_e32 v178, v1, v172
	s_waitcnt vmcnt(0)
	ds_write_b128 v171, v[4:7]
	global_load_dwordx4 v[4:7], v[8:9], off offset:160
	s_waitcnt vmcnt(0)
	ds_write_b128 v170, v[4:7]
	global_load_dwordx4 v[4:7], v[8:9], off offset:192
	s_waitcnt vmcnt(0)
	ds_write_b128 v169, v[4:7]
	global_load_dwordx4 v[4:7], v[8:9], off offset:224
	s_waitcnt vmcnt(0)
	ds_write_b128 v168, v[4:7]
	global_load_dwordx4 v[4:7], v[8:9], off offset:256
	s_waitcnt vmcnt(0)
	ds_write_b128 v171, v[4:7] offset:4096
	global_load_dwordx4 v[4:7], v[8:9], off offset:288
	s_waitcnt vmcnt(0)
	ds_write_b128 v170, v[4:7] offset:4096
	global_load_dwordx4 v[4:7], v[8:9], off offset:320
	s_waitcnt vmcnt(0)
	ds_write_b128 v169, v[4:7] offset:4096
	global_load_dwordx4 v[4:7], v[8:9], off offset:352
	s_waitcnt vmcnt(0)
	ds_write_b128 v168, v[4:7] offset:4096
	s_waitcnt vmcnt(0)
	s_waitcnt lgkmcnt(0)
	s_barrier
	ds_read_b128 v[4:7], v178 offset:32768
	ds_read_b128 v[8:11], v178 offset:36864
	s_waitcnt lgkmcnt(1)
	v_mfma_f32_32x32x16_bf16 v[36:51], v[4:7], v[126:129], 0
	v_add_u32_e32 v179, v1, v173
	ds_read_b128 v[12:15], v179 offset:32768
	ds_read_b128 v[16:19], v179 offset:36864
	s_waitcnt lgkmcnt(2)
	v_mfma_f32_32x32x16_bf16 v[20:35], v[8:11], v[126:129], 0
	s_waitcnt lgkmcnt(1)
	v_mfma_f32_32x32x16_bf16 v[36:51], v[12:15], v[122:125], v[36:51]
	v_add_u32_e32 v177, v1, v174
	ds_read_b128 v[4:7], v177 offset:32768
	ds_read_b128 v[8:11], v177 offset:36864
	s_waitcnt lgkmcnt(2)
	v_mfma_f32_32x32x16_bf16 v[20:35], v[16:19], v[122:125], v[20:35]
	s_waitcnt lgkmcnt(1)
	v_mfma_f32_32x32x16_bf16 v[36:51], v[4:7], v[118:121], v[36:51]
	v_add_u32_e32 v176, v1, v175
	ds_read_b128 v[12:15], v176 offset:32768
	ds_read_b128 v[16:19], v176 offset:36864
	s_waitcnt lgkmcnt(2)
	v_mfma_f32_32x32x16_bf16 v[20:35], v[8:11], v[118:121], v[20:35]
	s_waitcnt lgkmcnt(1)
	v_mfma_f32_32x32x16_bf16 v[36:51], v[12:15], v[114:117], v[36:51]
	ds_read_b128 v[4:7], v178 offset:40960
	ds_read_b128 v[8:11], v178 offset:45056
	ds_read_b128 v[64:67], v171
	s_waitcnt lgkmcnt(3)
	v_mfma_f32_32x32x16_bf16 v[20:35], v[16:19], v[114:117], v[20:35]
	s_waitcnt lgkmcnt(0)
	v_mfma_f32_32x32x16_bf16 v[36:51], v[4:7], v[64:67], v[36:51]
	ds_read_b128 v[12:15], v179 offset:40960
	ds_read_b128 v[16:19], v179 offset:45056
	ds_read_b128 v[68:71], v170
	v_mfma_f32_32x32x16_bf16 v[20:35], v[8:11], v[64:67], v[20:35]
	s_waitcnt lgkmcnt(0)
	v_mfma_f32_32x32x16_bf16 v[36:51], v[12:15], v[68:71], v[36:51]
	ds_read_b128 v[4:7], v177 offset:40960
	ds_read_b128 v[8:11], v177 offset:45056
	ds_read_b128 v[64:67], v169
	v_mfma_f32_32x32x16_bf16 v[20:35], v[16:19], v[68:71], v[20:35]
	s_waitcnt lgkmcnt(0)
	v_mfma_f32_32x32x16_bf16 v[36:51], v[4:7], v[64:67], v[36:51]
	ds_read_b128 v[12:15], v176 offset:40960
	ds_read_b128 v[16:19], v176 offset:45056
	ds_read_b128 v[68:71], v168
	v_mfma_f32_32x32x16_bf16 v[20:35], v[8:11], v[64:67], v[20:35]
	s_waitcnt lgkmcnt(0)
	v_mfma_f32_32x32x16_bf16 v[36:51], v[12:15], v[68:71], v[36:51]
	ds_read_b128 v[4:7], v178 offset:49152
	ds_read_b128 v[8:11], v178 offset:53248
	ds_read_b128 v[64:67], v171 offset:4096
	v_mfma_f32_32x32x16_bf16 v[20:35], v[16:19], v[68:71], v[20:35]
	s_waitcnt lgkmcnt(0)
	v_mfma_f32_32x32x16_bf16 v[36:51], v[4:7], v[64:67], v[36:51]
	ds_read_b128 v[12:15], v179 offset:49152
	ds_read_b128 v[16:19], v179 offset:53248
	ds_read_b128 v[68:71], v170 offset:4096
	v_mfma_f32_32x32x16_bf16 v[20:35], v[8:11], v[64:67], v[20:35]
	s_waitcnt lgkmcnt(0)
	v_mfma_f32_32x32x16_bf16 v[36:51], v[12:15], v[68:71], v[36:51]
	ds_read_b128 v[4:7], v177 offset:49152
	ds_read_b128 v[8:11], v177 offset:53248
	ds_read_b128 v[64:67], v169 offset:4096
	v_mfma_f32_32x32x16_bf16 v[20:35], v[16:19], v[68:71], v[20:35]
	s_waitcnt lgkmcnt(0)
	v_mfma_f32_32x32x16_bf16 v[36:51], v[4:7], v[64:67], v[36:51]
	ds_read_b128 v[12:15], v176 offset:49152
	ds_read_b128 v[16:19], v176 offset:53248
	ds_read_b128 v[68:71], v168 offset:4096
	v_mfma_f32_32x32x16_bf16 v[20:35], v[8:11], v[64:67], v[20:35]
	s_waitcnt lgkmcnt(0)
	v_mfma_f32_32x32x16_bf16 v[36:51], v[12:15], v[68:71], v[36:51]
	v_mfma_f32_32x32x16_bf16 v[20:35], v[16:19], v[68:71], v[20:35]
	s_nop 10
	v_max_f32_e32 v1, v37, v37
	v_max_f32_e32 v2, v36, v36
	v_max_f32_e32 v1, v2, v1
	v_max3_f32 v2, v38, v39, v21
	v_max3_f32 v1, v1, v20, v22
	v_max3_f32 v1, v1, v23, v40
	v_max3_f32 v2, v2, v42, v43
	v_max3_f32 v1, v1, v41, v24
	v_max3_f32 v2, v2, v26, v27
	v_max3_f32 v1, v1, v25, v44
	v_max3_f32 v2, v2, v46, v47
	v_max3_f32 v1, v1, v45, v28
	v_max3_f32 v2, v2, v30, v31
	v_max3_f32 v1, v1, v29, v48
	v_max3_f32 v2, v2, v50, v51
	v_max3_f32 v1, v1, v49, v32
	v_max3_f32 v2, v2, v34, v35
	v_max3_f32 v1, v1, v33, v2
	v_mov_b32_e32 v2, v1
	s_nop 1
	v_permlane32_swap_b32_e32 v1, v2
	v_max_f32_e32 v2, v2, v2
	v_max_f32_e32 v1, v1, v1
	v_max_f32_e32 v1, v1, v2
	v_add_f32_e32 v2, 0x7149f2ca, v1
	v_cmp_ge_f32_e32 vcc, s3, v2
	s_cmp_eq_u64 vcc, exec
	s_cbranch_scc0 .LBB0_794
	v_mov_b32_e32 v140, 0xf149f2ca
	v_mov_b32_e32 v180, 1.0

; __device__ __forceinline__ unsigned xb_ld(unsigned* p)              { return __hip_atomic_load(p, __ATOMIC_RELAXED, __HIP_MEMORY_SCOPE_AGENT); }
; __device__ __forceinline__ void xcd_barrier_complete(unsigned* bar, unsigned x, unsigned& nloc, unsigned& nx) {
;     const unsigned G = gridDim.x * gridDim.y * gridDim.z;
;     unsigned sum, cnt, mine, sp = 0u;
;     for (;;) {
;         sum = 0u; cnt = 0u; mine = 0u;
; #pragma unroll
;         for (unsigned j = 0; j < 16; ++j) { const unsigned c = xb_ld(&bar[XB_XCNT(j)]); sum += c; cnt += (c > 0u) ? 1u : 0u; mine = (j == x) ? c : mine; }
;         if (sum == G) break;
;         __builtin_amdgcn_s_sleep(1);
;         if ((++sp & 255u) == 0u) { if (xb_ld(&bar[XB_TMO])) break; if (sp > XB_SPIN_CAP) { atomicAdd(&bar[XB_TMO], 1u); break; } }
;     }
;     nloc = mine > 0u ? mine : 1u; nx = cnt > 0u ? cnt : 1u;
; }
; __device__ __forceinline__ void xcd_barrier(const XcdBarrier& b) {
;     asm volatile("s_waitcnt vmcnt(0)" ::: "memory");
;     __syncthreads();
;     if (threadIdx.x == 0) {
;         unsigned* bar = b.bar;
;         __builtin_amdgcn_s_waitcnt(0);
;         unsigned nloc = b.st[0], nx = b.st[1];
;         if (nloc == 0u) { xcd_barrier_complete(bar, b.x, nloc, nx); b.st[0] = nloc; b.st[1] = nx; }
.LBB0_796:
	s_setprio 0
	s_cmp_gt_i32 s31, 4
	s_cselect_b64 s[0:1], -1, 0
	s_and_b64 s[2:3], s[4:5], s[0:1]
	s_andn2_b64 vcc, exec, s[2:3]
	s_cbranch_vccnz .LBB0_846
	s_waitcnt vmcnt(0)
	v_cmp_eq_u32_e32 vcc, 0, v0
	s_waitcnt lgkmcnt(0)
	s_barrier
	s_and_saveexec_b64 s[4:5], vcc
	s_cbranch_execz .LBB0_845
	v_readlane_b32 s2, v247, 5
	s_waitcnt vmcnt(0) expcnt(0) lgkmcnt(0)
	s_nop 0
	v_mov_b32_e32 v1, s2
	ds_read_b32 v3, v1
	ds_read_b32 v1, v1 offset:4
	s_waitcnt lgkmcnt(1)
	v_cmp_ne_u32_e32 vcc, 0, v3
	s_cbranch_vccnz .LBB0_813
	v_readlane_b32 s6, v247, 0
	v_readlane_b32 s7, v247, 1
	s_load_dwordx2 s[2:3], s[6:7], 0x4
	s_add_u32 s6, s28, 0x4200
	s_addc_u32 s7, s29, 0
	s_add_u32 s8, s28, 0x4400
	s_addc_u32 s9, s29, 0
	s_add_u32 s10, s28, 0x4500
	s_addc_u32 s11, s29, 0
	s_add_u32 s22, s28, 0x4600
	s_addc_u32 s23, s29, 0
	s_add_u32 s36, s28, 0x4700
	s_addc_u32 s37, s29, 0
	s_add_u32 s38, s28, 0x4800
	s_addc_u32 s39, s29, 0
	s_add_u32 s40, s28, 0x4900
	s_addc_u32 s41, s29, 0
	s_add_u32 s42, s28, 0x4a00
	s_addc_u32 s43, s29, 0
	s_add_u32 s44, s28, 0x4b00
	s_addc_u32 s45, s29, 0
	s_add_u32 s46, s28, 0x4c00
	s_addc_u32 s47, s29, 0
	s_add_u32 s48, s28, 0x4d00
	s_addc_u32 s49, s29, 0
	s_add_u32 s50, s28, 0x4e00
	s_addc_u32 s51, s29, 0
	s_add_u32 s54, s28, 0x4f00
	s_addc_u32 s55, s29, 0
	s_add_u32 s58, s28, 0x5000
	s_addc_u32 s59, s29, 0
	s_add_u32 s62, s28, 0x5100
	s_addc_u32 s63, s29, 0
	s_add_u32 s64, s28, 0x5200
	s_addc_u32 s65, s29, 0
	s_waitcnt lgkmcnt(0)
	s_mul_i32 s2, s2, s33
	s_add_u32 s66, s28, 0x5300
	s_mul_i32 s2, s2, s3
	s_addc_u32 s67, s29, 0
	s_mov_b32 s3, 1
	v_mov_b32_e32 v17, 0
	s_branch .LBB0_801
